# one static s_setprio 1 for waves 4-7 across the MLA tile loop (reset at unit end)
# speedup vs baseline: 1.0210x; 1.0210x over previous
.Lmla_p_nomask:
	v_max3_f32 v251, v64, v65, v66
	v_max3_f32 v251, v251, v67, v68
	v_max3_f32 v251, v251, v69, v70
	v_max3_f32 v251, v251, v71, v72
	v_max3_f32 v251, v251, v73, v74
	v_max3_f32 v251, v251, v75, v76
	v_max3_f32 v251, v251, v77, v78
	v_max_f32_e32 v251, v251, v79
	v_max3_f32 v252, v80, v81, v82
	v_max3_f32 v252, v252, v83, v84
	v_max3_f32 v252, v252, v85, v86
	v_max3_f32 v252, v252, v87, v88
	v_max3_f32 v252, v252, v89, v90
	v_max3_f32 v252, v252, v91, v92
	v_max3_f32 v252, v252, v93, v94
	v_max_f32_e32 v252, v252, v95
	v_max_f32_e32 v251, v251, v252
	v_mov_b32_e32 v252, v251
	s_nop 1
	v_permlane32_swap_b32_e32 v251, v252
	v_max_f32_e32 v251, v251, v252
	v_mov_b32_e32 v212, v251
	v_sub_f32_e32 v64, v64, v251
	v_sub_f32_e32 v65, v65, v251
	v_sub_f32_e32 v66, v66, v251
	v_sub_f32_e32 v67, v67, v251
	v_sub_f32_e32 v68, v68, v251
	v_sub_f32_e32 v69, v69, v251
	v_sub_f32_e32 v70, v70, v251
	v_sub_f32_e32 v71, v71, v251
	v_sub_f32_e32 v72, v72, v251
	v_sub_f32_e32 v73, v73, v251
	v_sub_f32_e32 v74, v74, v251
	v_sub_f32_e32 v75, v75, v251
	v_sub_f32_e32 v76, v76, v251
	v_sub_f32_e32 v77, v77, v251
	v_sub_f32_e32 v78, v78, v251
	v_sub_f32_e32 v79, v79, v251
	v_sub_f32_e32 v80, v80, v251
	v_sub_f32_e32 v81, v81, v251
	v_sub_f32_e32 v82, v82, v251
	v_sub_f32_e32 v83, v83, v251
	v_sub_f32_e32 v84, v84, v251
	v_sub_f32_e32 v85, v85, v251
	v_sub_f32_e32 v86, v86, v251
	v_sub_f32_e32 v87, v87, v251
	v_sub_f32_e32 v88, v88, v251
	v_sub_f32_e32 v89, v89, v251
	v_sub_f32_e32 v90, v90, v251
	v_sub_f32_e32 v91, v91, v251
	v_sub_f32_e32 v92, v92, v251
	v_sub_f32_e32 v93, v93, v251
	v_sub_f32_e32 v94, v94, v251
	v_sub_f32_e32 v95, v95, v251
	v_xor_b32_e32 v48, 0x80000000, v251
	v_mov_b32_e32 v49, v48
	v_mov_b32_e32 v50, v48
	v_mov_b32_e32 v51, v48
	v_mov_b32_e32 v52, v48
	v_mov_b32_e32 v53, v48
	v_mov_b32_e32 v54, v48
	v_mov_b32_e32 v55, v48
	v_mov_b32_e32 v56, v48
	v_mov_b32_e32 v57, v48
	v_mov_b32_e32 v58, v48
	v_mov_b32_e32 v59, v48
	v_mov_b32_e32 v60, v48
	v_mov_b32_e32 v61, v48
	v_mov_b32_e32 v62, v48
	v_mov_b32_e32 v63, v48
	s_waitcnt lgkmcnt(0)
	s_barrier
	s_cmp_lt_u32 s39, 4
	s_cbranch_scc1 .Lmla_noprio
	s_setprio 1
.Lmla_noprio:
.Lmla_loop:
.Lmla_it0:
	s_add_i32 s42, s65, 3
	s_min_u32 s42, s42, s44
	s_lshl_b64 s[6:7], s[42:43], 17
	v_lshl_add_u64 v[242:243], v[190:191], 0, s[6:7]
	s_lshl_b64 s[6:7], s[42:43], 12
	v_lshl_add_u64 v[244:245], v[194:195], 0, s[6:7]
	s_add_i32 s42, s65, 2
	s_min_u32 s42, s42, s44
	s_lshl_b64 s[6:7], s[42:43], 17
	v_lshl_add_u64 v[246:247], v[192:193], 0, s[6:7]
	global_load_dwordx4 v[6:9], v[242:243], off
	global_load_dwordx4 v[10:13], v[246:247], off
	global_load_dwordx4 v[2:5], v[244:245], off
	s_cmp_ge_u32 s65, s45
	s_cbranch_scc1 .Lmla_skip0
	s_add_i32 s41, s65, 1
	s_cmp_ge_u32 s41, s64
	s_cselect_b32 s7, 1, 0
	s_cmp_lt_u32 s41, s45
	s_cselect_b32 s26, 1, 0
	s_and_b32 s56, s7, s26
	s_lshl_b32 s27, s41, 6
	ds_read_b128 v[164:167], v210 offset:25600
	ds_read_b128 v[168:171], v210 offset:25632
	ds_read_b128 v[172:175], v210 offset:25664
	ds_read_b128 v[214:217], v210 offset:25696
	ds_read_b128 v[218:221], v210 offset:25728
	ds_read_b128 v[222:225], v210 offset:25760
	v_exp_f32_e32 v64, v64
	v_exp_f32_e32 v65, v65
	v_exp_f32_e32 v66, v66
	v_exp_f32_e32 v67, v67
	s_waitcnt lgkmcnt(5)
	v_mfma_f32_32x32x16_bf16 v[132:147], v[164:167], v[96:99], v[48:63]
	ds_read_b128 v[164:167], v210 offset:32256
	v_add_f32_e32 v14, v64, v65
	v_add_f32_e32 v15, v66, v67
	v_exp_f32_e32 v68, v68
	v_exp_f32_e32 v69, v69
	s_waitcnt lgkmcnt(5)
	v_mfma_f32_32x32x16_bf16 v[132:147], v[168:171], v[100:103], v[132:147]
	ds_read_b128 v[168:171], v210 offset:32288
	v_exp_f32_e32 v70, v70
	v_exp_f32_e32 v71, v71
	v_add_f32_e32 v14, v14, v15
	v_add_f32_e32 v15, v68, v69
	s_waitcnt lgkmcnt(5)
	v_mfma_f32_32x32x16_bf16 v[132:147], v[172:175], v[104:107], v[132:147]
	ds_read_b128 v[172:175], v210 offset:32320
	v_add_f32_e32 v213, v70, v71
	v_cvt_pk_bf16_f32 v64, v64, v65
	v_cvt_pk_bf16_f32 v65, v66, v67
	v_cvt_pk_bf16_f32 v66, v68, v69
	v_cvt_pk_bf16_f32 v67, v70, v71
	s_waitcnt lgkmcnt(5)
	v_mfma_f32_32x32x16_bf16 v[132:147], v[214:217], v[108:111], v[132:147]
	ds_read_b128 v[214:217], v210 offset:32352
	v_exp_f32_e32 v72, v72
	v_exp_f32_e32 v73, v73
	v_exp_f32_e32 v74, v74
	v_exp_f32_e32 v75, v75
	s_waitcnt lgkmcnt(5)
	v_mfma_f32_32x32x16_bf16 v[132:147], v[218:221], v[112:115], v[132:147]
	ds_read_b128 v[218:221], v210 offset:32384
	v_add_f32_e32 v14, v14, v15
	v_add_f32_e32 v14, v14, v213
	v_exp_f32_e32 v76, v76
	v_exp_f32_e32 v77, v77
	s_waitcnt lgkmcnt(5)
	v_mfma_f32_32x32x16_bf16 v[132:147], v[222:225], v[116:119], v[132:147]
	ds_read_b128 v[222:225], v210 offset:32416
	v_exp_f32_e32 v78, v78
	v_exp_f32_e32 v79, v79
	v_add_f32_e32 v15, v72, v73
	v_add_f32_e32 v213, v74, v75
	s_waitcnt lgkmcnt(5)
	v_mfma_f32_32x32x16_bf16 v[148:163], v[164:167], v[96:99], v[48:63]
	ds_read_b64_tr_b16 v[226:227], v211 offset:13312
	ds_read_b64_tr_b16 v[228:229], v211 offset:14848
	v_add_f32_e32 v248, v76, v77
	v_add_f32_e32 v249, v78, v79
	v_cvt_pk_bf16_f32 v68, v72, v73
	v_cvt_pk_bf16_f32 v69, v74, v75
	v_cvt_pk_bf16_f32 v70, v76, v77
	v_cvt_pk_bf16_f32 v71, v78, v79
	s_waitcnt lgkmcnt(6)
	v_mfma_f32_32x32x16_bf16 v[148:163], v[168:171], v[100:103], v[148:163]
	ds_read_b64_tr_b16 v[230:231], v211 offset:13376
	ds_read_b64_tr_b16 v[232:233], v211 offset:14912
	v_add_f32_e32 v15, v15, v213
	v_add_f32_e32 v248, v248, v249
	v_exp_f32_e32 v80, v80
	v_exp_f32_e32 v81, v81
	s_waitcnt lgkmcnt(7)
	v_mfma_f32_32x32x16_bf16 v[148:163], v[172:175], v[104:107], v[148:163]
	ds_read_b64_tr_b16 v[234:235], v211 offset:16384
	ds_read_b64_tr_b16 v[236:237], v211 offset:17920
	v_exp_f32_e32 v82, v82
	v_exp_f32_e32 v83, v83
	v_add_f32_e32 v14, v14, v15
	v_add_f32_e32 v14, v14, v248
	s_waitcnt lgkmcnt(8)
	v_mfma_f32_32x32x16_bf16 v[148:163], v[214:217], v[108:111], v[148:163]
	ds_read_b64_tr_b16 v[238:239], v211 offset:16448
	ds_read_b64_tr_b16 v[240:241], v211 offset:17984
	v_add_f32_e32 v15, v80, v81
	v_add_f32_e32 v213, v82, v83
	v_exp_f32_e32 v84, v84
	v_exp_f32_e32 v85, v85
	s_waitcnt lgkmcnt(9)
	v_mfma_f32_32x32x16_bf16 v[148:163], v[218:221], v[112:115], v[148:163]
	v_exp_f32_e32 v86, v86
	v_exp_f32_e32 v87, v87
	v_add_f32_e32 v15, v15, v213
	v_add_f32_e32 v213, v84, v85
	s_waitcnt lgkmcnt(8)
	v_mfma_f32_32x32x16_bf16 v[148:163], v[222:225], v[116:119], v[148:163]
	v_add_f32_e32 v248, v86, v87
	v_cvt_pk_bf16_f32 v80, v80, v81
	v_cvt_pk_bf16_f32 v81, v82, v83
	v_cvt_pk_bf16_f32 v82, v84, v85
	v_cvt_pk_bf16_f32 v83, v86, v87
	s_waitcnt lgkmcnt(6)
	v_mfma_f32_32x32x16_bf16 v[32:47], v[226:229], v[64:67], v[32:47]
	ds_read_b64_tr_b16 v[226:227], v211 offset:19456
	ds_read_b64_tr_b16 v[228:229], v211 offset:20992
	v_exp_f32_e32 v88, v88
	v_exp_f32_e32 v89, v89
	v_exp_f32_e32 v90, v90
	v_exp_f32_e32 v91, v91
	s_waitcnt lgkmcnt(6)
	v_mfma_f32_32x32x16_bf16 v[16:31], v[230:233], v[64:67], v[16:31]
	ds_read_b64_tr_b16 v[230:231], v211 offset:19520
	ds_read_b64_tr_b16 v[232:233], v211 offset:21056
	v_add_f32_e32 v213, v213, v248
	v_add_f32_e32 v15, v15, v213
	v_exp_f32_e32 v92, v92
	v_exp_f32_e32 v93, v93
	s_waitcnt lgkmcnt(6)
	v_mfma_f32_32x32x16_bf16 v[32:47], v[234:237], v[68:71], v[32:47]
	ds_read_b64_tr_b16 v[234:235], v211 offset:22528
	ds_read_b64_tr_b16 v[236:237], v211 offset:24064
	v_exp_f32_e32 v94, v94
	v_exp_f32_e32 v95, v95
	v_add_f32_e32 v213, v88, v89
	v_add_f32_e32 v248, v90, v91
	s_waitcnt lgkmcnt(6)
	v_mfma_f32_32x32x16_bf16 v[16:31], v[238:241], v[68:71], v[16:31]
	ds_read_b64_tr_b16 v[238:239], v211 offset:22592
	ds_read_b64_tr_b16 v[240:241], v211 offset:24128
	s_cmp_lg_u32 s56, 0
	s_cbranch_scc1 .Lmla_mask0

; __device__ __forceinline__ void mla_unit(int h, int qb, const bf16_t* __restrict__ Qm, const bf16_t* __restrict__ Km, const bf16_t* __restrict__ Kr, const bf16_t* __restrict__ Vm, bf16_t* ZM, LAS char* lds) {
;     ...
;     for (int t = 0; t < NT; t += 2) {
;         MLA_STEP(t, gknA, gvA, gkrA, gknB, gvB, gkrB);
;         MLA_STEP(t + 1, gknB, gvB, gkrB, gknA, gvA, gkrA);
;     }
.Lmla_end1:
	s_add_i32 s65, s65, 2
	s_cmp_lt_u32 s65, s40
	s_cbranch_scc1 .Lmla_loop
	s_setprio 0
	s_waitcnt vmcnt(3)
	s_branch .LBB0_741
